# FFN-in GEMM main loop: last two of the six LDS-DMA pieces of the heavy super-phases issued from the middle of the wave's own MFMA block (wait vmcnt(8)->(6))
# baseline (speedup 1.0000x reference)
.LBB0_684:
	s_add_u32 s22, s20, 0xfffc0080
	s_addc_u32 s23, s21, -1
	s_add_i32 s51, 0, 0x10000
	s_cmp_eq_u32 s50, 12
	s_cselect_b32 s25, s15, s23
	s_cselect_b32 s24, s43, s22
	v_add_u32_e32 v140, s51, v143
	s_cselect_b32 s23, s13, s49
	s_cselect_b32 s22, s47, s48
	s_add_i32 s54, 0, 0x14000
	ds_read_b128 v[146:149], v140
	ds_read_b128 v[150:153], v140 offset:1024
	ds_read_b128 v[154:157], v140 offset:2048
	ds_read_b128 v[158:161], v140 offset:3072
	v_add_u32_e32 v140, s54, v143
	ds_read_b128 v[166:169], v140
	ds_read_b128 v[170:173], v140 offset:1024
	ds_read_b128 v[174:177], v140 offset:2048
	ds_read_b128 v[178:181], v140 offset:3072
	v_lshl_add_u64 v[140:141], s[20:21], 0, v[136:137]
	s_add_i32 m0, s36, 0xc000
	ds_read_b128 v[182:185], v145
	ds_read_b128 v[186:189], v145 offset:1024
	ds_read_b128 v[190:193], v145 offset:2048
	ds_read_b128 v[194:197], v145 offset:3072
	ds_read_b128 v[198:201], v145 offset:4096
	ds_read_b128 v[210:213], v145 offset:5120
	ds_read_b128 v[214:217], v145 offset:6144
	ds_read_b128 v[218:221], v145 offset:7168
	global_load_lds_dwordx4 v[140:141], off
	v_lshl_add_u64 v[140:141], s[20:21], 0, v[138:139]
	s_add_i32 m0, s36, 0xe000
	s_nop 0
	global_load_lds_dwordx4 v[140:141], off
	s_waitcnt vmcnt(8)
	s_waitcnt lgkmcnt(0)
	s_barrier
	s_setprio 1
	s_waitcnt lgkmcnt(0)
	v_mfma_f32_16x16x32_bf16 v[126:129], v[146:149], v[182:185], v[126:129]
	v_mfma_f32_16x16x32_bf16 v[118:121], v[154:157], v[182:185], v[118:121]
	v_mfma_f32_16x16x32_bf16 v[110:113], v[146:149], v[190:193], v[110:113]
	v_mfma_f32_16x16x32_bf16 v[102:105], v[154:157], v[190:193], v[102:105]
	v_mfma_f32_16x16x32_bf16 v[94:97], v[146:149], v[198:201], v[94:97]
	v_mfma_f32_16x16x32_bf16 v[86:89], v[154:157], v[198:201], v[86:89]
	v_mfma_f32_16x16x32_bf16 v[78:81], v[146:149], v[214:217], v[78:81]
	v_mfma_f32_16x16x32_bf16 v[70:73], v[154:157], v[214:217], v[70:73]
	v_mfma_f32_16x16x32_bf16 v[126:129], v[150:153], v[186:189], v[126:129]
	v_mfma_f32_16x16x32_bf16 v[118:121], v[158:161], v[186:189], v[118:121]
	v_mfma_f32_16x16x32_bf16 v[110:113], v[150:153], v[194:197], v[110:113]
	v_mfma_f32_16x16x32_bf16 v[102:105], v[158:161], v[194:197], v[102:105]
	v_mfma_f32_16x16x32_bf16 v[94:97], v[150:153], v[210:213], v[94:97]
	v_mfma_f32_16x16x32_bf16 v[86:89], v[158:161], v[210:213], v[86:89]
	v_mfma_f32_16x16x32_bf16 v[78:81], v[150:153], v[218:221], v[78:81]
	v_mfma_f32_16x16x32_bf16 v[70:73], v[158:161], v[218:221], v[70:73]
	s_setprio 0
	s_setprio 1
	v_mfma_f32_16x16x32_bf16 v[122:125], v[166:169], v[182:185], v[122:125]
	v_mfma_f32_16x16x32_bf16 v[114:117], v[174:177], v[182:185], v[114:117]
	v_mfma_f32_16x16x32_bf16 v[106:109], v[166:169], v[190:193], v[106:109]
	v_mfma_f32_16x16x32_bf16 v[98:101], v[174:177], v[190:193], v[98:101]
	v_mfma_f32_16x16x32_bf16 v[90:93], v[166:169], v[198:201], v[90:93]
	v_mfma_f32_16x16x32_bf16 v[82:85], v[174:177], v[198:201], v[82:85]
	v_mfma_f32_16x16x32_bf16 v[74:77], v[166:169], v[214:217], v[74:77]
	v_mfma_f32_16x16x32_bf16 v[66:69], v[174:177], v[214:217], v[66:69]
	v_mfma_f32_16x16x32_bf16 v[122:125], v[170:173], v[186:189], v[122:125]
	v_mfma_f32_16x16x32_bf16 v[114:117], v[178:181], v[186:189], v[114:117]
	v_mfma_f32_16x16x32_bf16 v[106:109], v[170:173], v[194:197], v[106:109]
	v_mfma_f32_16x16x32_bf16 v[98:101], v[178:181], v[194:197], v[98:101]
	v_mfma_f32_16x16x32_bf16 v[90:93], v[170:173], v[210:213], v[90:93]
	v_mfma_f32_16x16x32_bf16 v[82:85], v[178:181], v[210:213], v[82:85]
	v_mfma_f32_16x16x32_bf16 v[74:77], v[170:173], v[218:221], v[74:77]
	v_mfma_f32_16x16x32_bf16 v[66:69], v[178:181], v[218:221], v[66:69]
	s_setprio 0
	s_barrier
	s_add_i32 s51, s51, s29
	v_lshl_add_u64 v[140:141], s[22:23], 0, v[0:1]
	s_mov_b32 m0, s51
	ds_read_b128 v[182:185], v145 offset:16384
	ds_read_b128 v[186:189], v145 offset:17408
	ds_read_b128 v[190:193], v145 offset:18432
	ds_read_b128 v[194:197], v145 offset:19456
	ds_read_b128 v[198:201], v145 offset:20480
	ds_read_b128 v[210:213], v145 offset:21504
	ds_read_b128 v[214:217], v145 offset:22528
	ds_read_b128 v[218:221], v145 offset:23552
	global_load_lds_dwordx4 v[140:141], off
	s_add_i32 m0, s51, 0x2000
	s_add_u32 s52, s22, 0x40000
	v_lshl_add_u64 v[202:203], s[22:23], 0, v[130:131]
	s_addc_u32 s53, s23, 0
	s_add_i32 s51, s54, s29
	global_load_lds_dwordx4 v[202:203], off
	v_lshl_add_u64 v[206:207], s[52:53], 0, v[0:1]
	s_mov_b32 m0, s51
	v_lshl_add_u64 v[222:223], s[24:25], 0, v[132:133]
	global_load_lds_dwordx4 v[206:207], off
	v_lshl_add_u64 v[206:207], s[52:53], 0, v[130:131]
	s_add_i32 m0, s51, 0x2000
	s_nop 0
	global_load_lds_dwordx4 v[206:207], off
	s_waitcnt vmcnt(6)
	s_waitcnt lgkmcnt(0)
	s_barrier
	s_setprio 1
	s_waitcnt lgkmcnt(0)
	v_mfma_f32_16x16x32_bf16 v[62:65], v[146:149], v[182:185], v[62:65]
	v_mfma_f32_16x16x32_bf16 v[54:57], v[154:157], v[182:185], v[54:57]
	v_mfma_f32_16x16x32_bf16 v[46:49], v[146:149], v[190:193], v[46:49]
	v_mfma_f32_16x16x32_bf16 v[38:41], v[154:157], v[190:193], v[38:41]
	v_mfma_f32_16x16x32_bf16 v[30:33], v[146:149], v[198:201], v[30:33]
	v_mfma_f32_16x16x32_bf16 v[22:25], v[154:157], v[198:201], v[22:25]
	v_mfma_f32_16x16x32_bf16 v[14:17], v[146:149], v[214:217], v[14:17]
	v_mfma_f32_16x16x32_bf16 v[6:9], v[154:157], v[214:217], v[6:9]
	v_mfma_f32_16x16x32_bf16 v[62:65], v[150:153], v[186:189], v[62:65]
	v_mfma_f32_16x16x32_bf16 v[54:57], v[158:161], v[186:189], v[54:57]
	v_mfma_f32_16x16x32_bf16 v[46:49], v[150:153], v[194:197], v[46:49]
	v_mfma_f32_16x16x32_bf16 v[38:41], v[158:161], v[194:197], v[38:41]
	v_mfma_f32_16x16x32_bf16 v[30:33], v[150:153], v[210:213], v[30:33]
	v_mfma_f32_16x16x32_bf16 v[22:25], v[158:161], v[210:213], v[22:25]
	v_mfma_f32_16x16x32_bf16 v[14:17], v[150:153], v[218:221], v[14:17]
	v_mfma_f32_16x16x32_bf16 v[6:9], v[158:161], v[218:221], v[6:9]
	s_setprio 0
	v_lshl_add_u64 v[206:207], s[24:25], 0, v[134:135]
	s_mov_b32 m0, s36
	s_nop 0
	global_load_lds_dwordx4 v[206:207], off
	s_mov_b32 m0, s37
	s_nop 0
	global_load_lds_dwordx4 v[222:223], off
	s_setprio 1
	v_mfma_f32_16x16x32_bf16 v[58:61], v[166:169], v[182:185], v[58:61]
	v_mfma_f32_16x16x32_bf16 v[50:53], v[174:177], v[182:185], v[50:53]
	v_mfma_f32_16x16x32_bf16 v[42:45], v[166:169], v[190:193], v[42:45]
	v_mfma_f32_16x16x32_bf16 v[34:37], v[174:177], v[190:193], v[34:37]
	v_mfma_f32_16x16x32_bf16 v[26:29], v[166:169], v[198:201], v[26:29]
	v_mfma_f32_16x16x32_bf16 v[18:21], v[174:177], v[198:201], v[18:21]
	v_mfma_f32_16x16x32_bf16 v[10:13], v[166:169], v[214:217], v[10:13]
	v_mfma_f32_16x16x32_bf16 v[2:5], v[174:177], v[214:217], v[2:5]
	v_mfma_f32_16x16x32_bf16 v[58:61], v[170:173], v[186:189], v[58:61]
	v_mfma_f32_16x16x32_bf16 v[50:53], v[178:181], v[186:189], v[50:53]
	v_mfma_f32_16x16x32_bf16 v[42:45], v[170:173], v[194:197], v[42:45]
	v_mfma_f32_16x16x32_bf16 v[34:37], v[178:181], v[194:197], v[34:37]
	v_mfma_f32_16x16x32_bf16 v[26:29], v[170:173], v[210:213], v[26:29]
	v_mfma_f32_16x16x32_bf16 v[18:21], v[178:181], v[210:213], v[18:21]
	v_mfma_f32_16x16x32_bf16 v[10:13], v[170:173], v[218:221], v[10:13]
	v_mfma_f32_16x16x32_bf16 v[2:5], v[178:181], v[218:221], v[2:5]
	s_setprio 0
	s_barrier
	s_add_i32 s51, 0, 0x18000
	s_add_i32 s52, 0, 0x1c000
	v_add_u32_e32 v158, s51, v143
	v_add_u32_e32 v178, s52, v143
	ds_read_b128 v[146:149], v158
	ds_read_b128 v[150:153], v158 offset:1024
	ds_read_b128 v[154:157], v158 offset:2048
	ds_read_b128 v[158:161], v158 offset:3072
	ds_read_b128 v[166:169], v178
	ds_read_b128 v[170:173], v178 offset:1024
	ds_read_b128 v[174:177], v178 offset:2048
	ds_read_b128 v[178:181], v178 offset:3072
	s_add_u32 s24, s24, 0x40000
	s_addc_u32 s25, s25, 0
	s_mov_b32 m0, s38
	v_lshl_add_u64 v[224:225], s[24:25], 0, v[134:135]
	ds_read_b128 v[182:185], v145 offset:32768
	ds_read_b128 v[186:189], v145 offset:33792
	ds_read_b128 v[190:193], v145 offset:34816
	ds_read_b128 v[194:197], v145 offset:35840
	ds_read_b128 v[198:201], v145 offset:36864
	ds_read_b128 v[210:213], v145 offset:37888
	ds_read_b128 v[214:217], v145 offset:38912
	ds_read_b128 v[218:221], v145 offset:39936
	global_load_lds_dwordx4 v[224:225], off
	v_lshl_add_u64 v[224:225], s[24:25], 0, v[132:133]
	s_mov_b32 m0, s39
	s_nop 0
	global_load_lds_dwordx4 v[224:225], off
	s_waitcnt vmcnt(8)
	s_waitcnt lgkmcnt(0)
	s_barrier
	s_setprio 1
	s_waitcnt lgkmcnt(0)
	v_mfma_f32_16x16x32_bf16 v[126:129], v[146:149], v[182:185], v[126:129]
	v_mfma_f32_16x16x32_bf16 v[118:121], v[154:157], v[182:185], v[118:121]
	v_mfma_f32_16x16x32_bf16 v[110:113], v[146:149], v[190:193], v[110:113]
	v_mfma_f32_16x16x32_bf16 v[102:105], v[154:157], v[190:193], v[102:105]
	v_mfma_f32_16x16x32_bf16 v[94:97], v[146:149], v[198:201], v[94:97]
	v_mfma_f32_16x16x32_bf16 v[86:89], v[154:157], v[198:201], v[86:89]
	v_mfma_f32_16x16x32_bf16 v[78:81], v[146:149], v[214:217], v[78:81]
	v_mfma_f32_16x16x32_bf16 v[70:73], v[154:157], v[214:217], v[70:73]
	v_mfma_f32_16x16x32_bf16 v[126:129], v[150:153], v[186:189], v[126:129]
	v_mfma_f32_16x16x32_bf16 v[118:121], v[158:161], v[186:189], v[118:121]
	v_mfma_f32_16x16x32_bf16 v[110:113], v[150:153], v[194:197], v[110:113]
	v_mfma_f32_16x16x32_bf16 v[102:105], v[158:161], v[194:197], v[102:105]
	v_mfma_f32_16x16x32_bf16 v[94:97], v[150:153], v[210:213], v[94:97]
	v_mfma_f32_16x16x32_bf16 v[86:89], v[158:161], v[210:213], v[86:89]
	v_mfma_f32_16x16x32_bf16 v[78:81], v[150:153], v[218:221], v[78:81]
	v_mfma_f32_16x16x32_bf16 v[70:73], v[158:161], v[218:221], v[70:73]
	s_setprio 0
	s_setprio 1
	v_mfma_f32_16x16x32_bf16 v[122:125], v[166:169], v[182:185], v[122:125]
	v_mfma_f32_16x16x32_bf16 v[114:117], v[174:177], v[182:185], v[114:117]
	v_mfma_f32_16x16x32_bf16 v[106:109], v[166:169], v[190:193], v[106:109]
	v_mfma_f32_16x16x32_bf16 v[98:101], v[174:177], v[190:193], v[98:101]
	v_mfma_f32_16x16x32_bf16 v[90:93], v[166:169], v[198:201], v[90:93]
	v_mfma_f32_16x16x32_bf16 v[82:85], v[174:177], v[198:201], v[82:85]
	v_mfma_f32_16x16x32_bf16 v[74:77], v[166:169], v[214:217], v[74:77]
	v_mfma_f32_16x16x32_bf16 v[66:69], v[174:177], v[214:217], v[66:69]
	v_mfma_f32_16x16x32_bf16 v[122:125], v[170:173], v[186:189], v[122:125]
	v_mfma_f32_16x16x32_bf16 v[114:117], v[178:181], v[186:189], v[114:117]
	v_mfma_f32_16x16x32_bf16 v[106:109], v[170:173], v[194:197], v[106:109]
	v_mfma_f32_16x16x32_bf16 v[98:101], v[178:181], v[194:197], v[98:101]
	v_mfma_f32_16x16x32_bf16 v[90:93], v[170:173], v[210:213], v[90:93]
	v_mfma_f32_16x16x32_bf16 v[82:85], v[178:181], v[210:213], v[82:85]
	v_mfma_f32_16x16x32_bf16 v[74:77], v[170:173], v[218:221], v[74:77]
	v_mfma_f32_16x16x32_bf16 v[66:69], v[178:181], v[218:221], v[66:69]
	s_setprio 0
	s_barrier
	s_add_i32 s24, s51, s29
	v_lshl_add_u64 v[140:141], v[140:141], 0, s[4:5]
	s_mov_b32 m0, s24
	ds_read_b128 v[182:185], v145 offset:49152
	ds_read_b128 v[186:189], v145 offset:50176
	ds_read_b128 v[190:193], v145 offset:51200
	ds_read_b128 v[194:197], v145 offset:52224
	ds_read_b128 v[198:201], v145 offset:53248
	ds_read_b128 v[210:213], v145 offset:54272
	ds_read_b128 v[214:217], v145 offset:55296
	ds_read_b128 v[218:221], v145 offset:56320
	global_load_lds_dwordx4 v[140:141], off
	s_add_i32 m0, s24, 0x2000
	s_add_u32 s22, s22, 0x40080
	v_lshl_add_u64 v[140:141], v[202:203], 0, s[4:5]
	s_addc_u32 s23, s23, 0
	s_add_i32 s24, s52, s29
	global_load_lds_dwordx4 v[140:141], off
	v_lshl_add_u64 v[140:141], s[22:23], 0, v[0:1]
	s_mov_b32 m0, s24
	s_nop 0
	global_load_lds_dwordx4 v[140:141], off
	v_lshl_add_u64 v[140:141], s[22:23], 0, v[130:131]
	s_add_i32 m0, s24, 0x2000
	s_nop 0
	global_load_lds_dwordx4 v[140:141], off
	s_waitcnt vmcnt(6)
	s_waitcnt lgkmcnt(0)
	s_barrier
	s_setprio 1
	s_waitcnt lgkmcnt(0)
	v_mfma_f32_16x16x32_bf16 v[62:65], v[146:149], v[182:185], v[62:65]
	v_mfma_f32_16x16x32_bf16 v[54:57], v[154:157], v[182:185], v[54:57]
	v_mfma_f32_16x16x32_bf16 v[46:49], v[146:149], v[190:193], v[46:49]
	v_mfma_f32_16x16x32_bf16 v[38:41], v[154:157], v[190:193], v[38:41]
	v_mfma_f32_16x16x32_bf16 v[30:33], v[146:149], v[198:201], v[30:33]
	v_mfma_f32_16x16x32_bf16 v[22:25], v[154:157], v[198:201], v[22:25]
	v_mfma_f32_16x16x32_bf16 v[14:17], v[146:149], v[214:217], v[14:17]
	v_mfma_f32_16x16x32_bf16 v[6:9], v[154:157], v[214:217], v[6:9]
	v_mfma_f32_16x16x32_bf16 v[62:65], v[150:153], v[186:189], v[62:65]
	v_mfma_f32_16x16x32_bf16 v[54:57], v[158:161], v[186:189], v[54:57]
	v_mfma_f32_16x16x32_bf16 v[46:49], v[150:153], v[194:197], v[46:49]
	v_mfma_f32_16x16x32_bf16 v[38:41], v[158:161], v[194:197], v[38:41]
	v_mfma_f32_16x16x32_bf16 v[30:33], v[150:153], v[210:213], v[30:33]
	v_mfma_f32_16x16x32_bf16 v[22:25], v[158:161], v[210:213], v[22:25]
	v_mfma_f32_16x16x32_bf16 v[14:17], v[150:153], v[218:221], v[14:17]
	v_mfma_f32_16x16x32_bf16 v[6:9], v[158:161], v[218:221], v[6:9]
	s_setprio 0
	v_lshl_add_u64 v[140:141], v[206:207], 0, s[4:5]
	s_mov_b32 m0, s40
	s_nop 0
	global_load_lds_dwordx4 v[140:141], off
	v_lshl_add_u64 v[140:141], v[222:223], 0, s[4:5]
	s_mov_b32 m0, s41
	s_nop 0
	global_load_lds_dwordx4 v[140:141], off
	s_setprio 1
	v_mfma_f32_16x16x32_bf16 v[58:61], v[166:169], v[182:185], v[58:61]
	v_mfma_f32_16x16x32_bf16 v[50:53], v[174:177], v[182:185], v[50:53]
	v_mfma_f32_16x16x32_bf16 v[42:45], v[166:169], v[190:193], v[42:45]
	v_mfma_f32_16x16x32_bf16 v[34:37], v[174:177], v[190:193], v[34:37]
	v_mfma_f32_16x16x32_bf16 v[26:29], v[166:169], v[198:201], v[26:29]
	v_mfma_f32_16x16x32_bf16 v[18:21], v[174:177], v[198:201], v[18:21]
	v_mfma_f32_16x16x32_bf16 v[10:13], v[166:169], v[214:217], v[10:13]
	v_mfma_f32_16x16x32_bf16 v[2:5], v[174:177], v[214:217], v[2:5]
	v_mfma_f32_16x16x32_bf16 v[58:61], v[170:173], v[186:189], v[58:61]
	v_mfma_f32_16x16x32_bf16 v[50:53], v[178:181], v[186:189], v[50:53]
	v_mfma_f32_16x16x32_bf16 v[42:45], v[170:173], v[194:197], v[42:45]
	v_mfma_f32_16x16x32_bf16 v[34:37], v[178:181], v[194:197], v[34:37]
	v_mfma_f32_16x16x32_bf16 v[26:29], v[170:173], v[210:213], v[26:29]
	v_mfma_f32_16x16x32_bf16 v[18:21], v[178:181], v[210:213], v[18:21]
	v_mfma_f32_16x16x32_bf16 v[10:13], v[170:173], v[218:221], v[10:13]
	v_mfma_f32_16x16x32_bf16 v[2:5], v[178:181], v[218:221], v[2:5]
	s_setprio 0
	s_barrier
	s_add_i32 s50, s50, 2
	s_add_u32 s20, s20, 0x100
	s_addc_u32 s21, s21, 0
	s_add_u32 s48, s48, 0x100
	s_addc_u32 s49, s49, 0
	s_cmp_gt_u32 s50, 13
	s_cbranch_scc0 .LBB0_684
	s_and_b64 vcc, exec, s[10:11]
	s_cbranch_vccz .LBB0_687
	s_barrier
